# speedup vs baseline: 1.0239x; 1.0099x over previous
; #define LAS __attribute__((address_space(3)))
; #define a (*get_args())
; template <bool OUT>
; __device__ __forceinline__ void ssm_fast(KArgs ap, int l, LAS unsigned char* lds, const Ctx cx) {
;     ...
;     const bf16_t* z = (const bf16_t*)(a.ws + WS_Z); bf16_t* ypre = (bf16_t*)(a.ws + WS_YPRE); float* E = (float*)(a.ws + WS_E);
;     const unsigned char* tb = a.ws + WS_TAB + (size_t)l * TAB_STRIDE;
;     const int gw = cx.bid * 8 + wave, NGW = cx.nb * 8;
;     const int g = gw & 31, r = lane & 31, hh = lane >> 5, p = lane;
;     LAS unsigned char* BU = lds + wave * 16384;
;     const float are = ((const float*)(tb + TAB_A))[(g * 64 + p) * 2], aim = ((const float*)(tb + TAB_A))[(g * 64 + p) * 2 + 1];
;     bf16x8 bt[4];
; #pragma unroll
;     for (int nb = 0; nb < 4; ++nb) bt[nb] = *(const bf16x8*)((const bf16_t*)(tb + TAB_BT) + (g * 128 + nb * 32 + r) * 16 + 8 * hh);
;     bf16x8 ct[4]; float dsk = 0.f;
;     if (OUT) {
; #pragma unroll
;         for (int ks = 0; ks < 4; ++ks) ct[ks] = *(const bf16x8*)((const bf16_t*)(tb + TAB_CT) + (g * 16 + (lane & 15)) * 128 + ks * 32 + 8 * (lane >> 4));
;         dsk = a.in[I_SSM_D][l * 512 + g * 16 + (lane & 15)];
;     }
;     __syncthreads();
; #pragma unroll 1
;     for (int it = gw; it < BATCH * SSM_NC * 32; it += NGW) {
;         const size_t tok0 = (size_t)(it >> 5) * 128;
;         float sr = 0.f, si = 0.f;
;         if (OUT) { sr = E[(size_t)it * 128 + p]; si = E[(size_t)it * 128 + 64 + p]; }
; #pragma unroll 1
;         for (int sc = 0; sc < 4; ++sc) {
;             const size_t tk = tok0 + sc * 32;
.LBB0_167:
	s_mov_b64 s[0:1], s[78:79]
	s_load_dwordx2 s[0:1], s[0:1], 0xd8
	s_lshl_b32 s4, s57, 3
	s_add_i32 s4, s80, s4
	s_and_b32 s5, s4, 31
	v_readlane_b32 s6, v243, 19
	s_waitcnt lgkmcnt(0)
	s_add_u32 s6, s0, s6
	s_addc_u32 s7, s1, 0
	s_add_u32 s6, s6, 0x3e600000
	s_addc_u32 s7, s7, 0
	v_lshlrev_b32_e32 v2, 5, v86
	s_lshl_b32 s8, s5, 9
	v_lshl_add_u64 v[0:1], v[84:85], 1, s[6:7]
	v_lshl_or_b32 v152, s5, 12, v2
	v_lshl_or_b32 v4, v112, 3, s8
	v_lshl_add_u64 v[0:1], v[0:1], 0, v[152:153]
	s_mov_b64 s[8:9], 0x8000
	v_lshl_add_u64 v[2:3], v[0:1], 0, s[8:9]
	v_add_co_u32_e32 v0, vcc, 0x8000, v0
	s_cmpk_gt_i32 s4, 0x1fff
	s_nop 0
	v_addc_co_u32_e32 v1, vcc, 0, v1, vcc
	global_load_dwordx4 v[64:67], v[0:1], off
	global_load_dwordx2 v[80:81], v4, s[6:7]
	global_load_dwordx4 v[68:71], v[2:3], off offset:1024
	global_load_dwordx4 v[72:75], v[2:3], off offset:2048
	global_load_dwordx4 v[76:79], v[2:3], off offset:3072
	s_waitcnt vmcnt(0)
	s_barrier
	s_cbranch_scc1 .LBB0_174
	s_lshl_b32 s6, s80, 14
	s_add_i32 s6, s6, 0
	v_lshlrev_b32_e32 v152, 2, v112
	v_lshlrev_b32_e32 v0, 11, v87
	v_lshlrev_b32_e32 v1, 2, v86
	s_lshl_b32 s5, s5, 4
	v_add_u32_e32 v94, s6, v152
	v_add3_u32 v87, s6, v0, v1
	v_lshl_add_u64 v[0:1], s[0:1], 0, v[152:153]
	s_mov_b64 s[6:7], 0x3e000000
	s_lshl_b32 s8, s55, 3
	v_lshl_add_u64 v[82:83], v[0:1], 0, s[6:7]
	v_pk_mov_b32 v[88:89], v[80:81], v[80:81] op_sel:[1,0]
	s_lshl_b32 s6, s5, 1
	s_mov_b32 s58, 0x2c000
	s_mov_b32 s59, 0

; #define LAS __attribute__((address_space(3)))
; #define MFMA32(a_, b_, c_) __builtin_amdgcn_mfma_f32_32x32x16_bf16((a_), (b_), (c_), 0, 0, 0)
; __device__ __forceinline__ int crow(int reg, int h) { return (reg & 3) + 8 * (reg >> 2) + 4 * h; }
; #define WAVE_FENCE() asm volatile("s_waitcnt lgkmcnt(0)" ::: "memory")
; template <bool OUT>
; __device__ __forceinline__ void ssm_fast(KArgs ap, int l, LAS unsigned char* lds, const Ctx cx) {
;     ...
;         for (int sc = 0; sc < 4; ++sc) {
;             const size_t tk = tok0 + sc * 32;
;             const bf16x8 uf = *(const bf16x8*)(z + (tk + r) * DIN + ZS + g * 16 + 8 * hh);
;             bf16_t uv[2][4];
;             if (OUT) {
; #pragma unroll
;                 for (int tbk = 0; tbk < 2; ++tbk)
; #pragma unroll
;                     for (int j = 0; j < 4; ++j) uv[tbk][j] = z[(tk + tbk * 16 + 4 * (lane >> 4) + j) * DIN + ZS + g * 16 + (lane & 15)];
;             }
;             WAVE_FENCE();
; #pragma unroll
;             for (int nb = 0; nb < 4; ++nb) { f32x16 c;
; #pragma unroll
;                 for (int i = 0; i < 16; ++i) c[i] = 0.f;
;                 c = MFMA32(uf, bt[nb], c);
; #pragma unroll
;                 for (int i = 0; i < 16; ++i) *(LAS float*)(BU + (crow(i, hh) * 128 + nb * 32 + r) * 4) = c[i]; }
;             WAVE_FENCE();
; #pragma unroll 4
;             for (int t = 0; t < 32; ++t) {
;                 const float br = *(const LAS float*)(BU + (t * 128 + p) * 4), bi = *(const LAS float*)(BU + (t * 128 + 64 + p) * 4);
;                 const float nr = are * sr - aim * si + br, ni = are * si + aim * sr + bi; sr = nr; si = ni;
.LBB0_170:
	s_lshl_b32 s76, s5, 5
	v_lshl_add_u64 v[0:1], v[90:91], 0, s[76:77]
	v_mov_b64_e32 v[2:3], s[0:1]
	s_movk_i32 s7, 0x1600
	v_mad_u64_u32 v[2:3], s[10:11], v0, s7, v[2:3]
	v_mad_i32_i24 v3, v1, s7, v3
	s_mov_b32 s7, s77
	v_lshl_add_u64 v[0:1], v[2:3], 0, s[6:7]
	v_lshl_add_u64 v[0:1], v[84:85], 1, v[0:1]
	v_add_co_u32_e32 v0, vcc, 0x13000000, v0
	v_add_u32_e32 v95, 0x400, v87
	s_nop 0
	v_addc_co_u32_e32 v1, vcc, 0, v1, vcc
	s_cmp_lg_u32 s5, 0
	s_cbranch_scc1 .Lssma_have_u
	global_load_dwordx4 v[102:105], v[0:1], off offset:2560
.Lssma_have_u:
	v_lshl_add_u64 v[106:107], v[0:1], 0, s[58:59]
	v_add_u32_e32 v96, 0x1000, v87
	v_add_u32_e32 v97, 0x1400, v87
	v_add_u32_e32 v98, 0x2000, v87
	v_add_u32_e32 v99, 0x2400, v87
	v_add_u32_e32 v100, 0x3000, v87
	v_add_u32_e32 v101, 0x3400, v87
	s_waitcnt lgkmcnt(0)
	s_mov_b32 s7, 0
	s_waitcnt vmcnt(0)
	v_mfma_f32_32x32x16_bf16 v[0:15], v[102:105], v[64:67], 0
	v_mfma_f32_32x32x16_bf16 v[16:31], v[102:105], v[68:71], 0
	v_mfma_f32_32x32x16_bf16 v[32:47], v[102:105], v[72:75], 0
	v_mfma_f32_32x32x16_bf16 v[48:63], v[102:105], v[76:79], 0
	s_nop 9
	s_cmp_eq_u32 s5, 3
	s_cbranch_scc1 .Lssma_no_pf
	global_load_dwordx4 v[102:105], v[106:107], off offset:2560
.Lssma_no_pf:
	s_waitcnt lgkmcnt(0)
.LBB0_171:
	v_permlane32_swap_b32_e32 v0, v16
	v_permlane32_swap_b32_e32 v1, v17
	v_permlane32_swap_b32_e32 v2, v18
	v_permlane32_swap_b32_e32 v3, v19
	v_permlane32_swap_b32_e32 v4, v20
	v_permlane32_swap_b32_e32 v5, v21
	v_permlane32_swap_b32_e32 v6, v22
	v_permlane32_swap_b32_e32 v7, v23
	v_permlane32_swap_b32_e32 v8, v24
	v_permlane32_swap_b32_e32 v9, v25
	v_permlane32_swap_b32_e32 v10, v26
	v_permlane32_swap_b32_e32 v11, v27
	v_permlane32_swap_b32_e32 v12, v28
	v_permlane32_swap_b32_e32 v13, v29
	v_permlane32_swap_b32_e32 v14, v30
	v_permlane32_swap_b32_e32 v15, v31
	v_permlane32_swap_b32_e32 v32, v48
	v_permlane32_swap_b32_e32 v33, v49
	v_permlane32_swap_b32_e32 v34, v50
	v_permlane32_swap_b32_e32 v35, v51
	v_permlane32_swap_b32_e32 v36, v52
	v_permlane32_swap_b32_e32 v37, v53
	v_permlane32_swap_b32_e32 v38, v54
	v_permlane32_swap_b32_e32 v39, v55
	v_permlane32_swap_b32_e32 v40, v56
	v_permlane32_swap_b32_e32 v41, v57
	v_permlane32_swap_b32_e32 v42, v58
	v_permlane32_swap_b32_e32 v43, v59
	v_permlane32_swap_b32_e32 v44, v60
	v_permlane32_swap_b32_e32 v45, v61
	v_permlane32_swap_b32_e32 v46, v62
	v_permlane32_swap_b32_e32 v47, v63
	v_mul_f32_e32 v113, v81, v93
	v_mul_f32_e32 v115, v80, v93
	v_fma_f32 v114, v80, v92, -v113
	v_fma_f32 v116, v81, v92, v115
	v_add_f32_e32 v92, v114, v0
	v_add_f32_e32 v93, v116, v32
	v_mul_f32_e32 v113, v81, v93
	v_mul_f32_e32 v115, v80, v93
	v_fma_f32 v114, v80, v92, -v113
	v_fma_f32 v116, v81, v92, v115
	v_add_f32_e32 v92, v114, v1
	v_add_f32_e32 v93, v116, v33
	v_mul_f32_e32 v113, v81, v93
	v_mul_f32_e32 v115, v80, v93
	v_fma_f32 v114, v80, v92, -v113
	v_fma_f32 v116, v81, v92, v115
	v_add_f32_e32 v92, v114, v2
	v_add_f32_e32 v93, v116, v34
	v_mul_f32_e32 v113, v81, v93
	v_mul_f32_e32 v115, v80, v93
	v_fma_f32 v114, v80, v92, -v113
	v_fma_f32 v116, v81, v92, v115
	v_add_f32_e32 v92, v114, v3
	v_add_f32_e32 v93, v116, v35
	v_mul_f32_e32 v113, v81, v93
	v_mul_f32_e32 v115, v80, v93
	v_fma_f32 v114, v80, v92, -v113
	v_fma_f32 v116, v81, v92, v115
	v_add_f32_e32 v92, v114, v16
	v_add_f32_e32 v93, v116, v48
	v_mul_f32_e32 v113, v81, v93
	v_mul_f32_e32 v115, v80, v93
	v_fma_f32 v114, v80, v92, -v113
	v_fma_f32 v116, v81, v92, v115
	v_add_f32_e32 v92, v114, v17
	v_add_f32_e32 v93, v116, v49
	v_mul_f32_e32 v113, v81, v93
	v_mul_f32_e32 v115, v80, v93
	v_fma_f32 v114, v80, v92, -v113
	v_fma_f32 v116, v81, v92, v115
	v_add_f32_e32 v92, v114, v18
	v_add_f32_e32 v93, v116, v50
	v_mul_f32_e32 v113, v81, v93
	v_mul_f32_e32 v115, v80, v93
	v_fma_f32 v114, v80, v92, -v113
	v_fma_f32 v116, v81, v92, v115
	v_add_f32_e32 v92, v114, v19
	v_add_f32_e32 v93, v116, v51
	v_mul_f32_e32 v113, v81, v93
	v_mul_f32_e32 v115, v80, v93
	v_fma_f32 v114, v80, v92, -v113
	v_fma_f32 v116, v81, v92, v115
	v_add_f32_e32 v92, v114, v4
	v_add_f32_e32 v93, v116, v36
	v_mul_f32_e32 v113, v81, v93
	v_mul_f32_e32 v115, v80, v93
	v_fma_f32 v114, v80, v92, -v113
	v_fma_f32 v116, v81, v92, v115
	v_add_f32_e32 v92, v114, v5
	v_add_f32_e32 v93, v116, v37
	v_mul_f32_e32 v113, v81, v93
	v_mul_f32_e32 v115, v80, v93
; #define LAS __attribute__((address_space(3)))
; __device__ __forceinline__ unsigned f2bf(float f) { unsigned u = __builtin_bit_cast(unsigned, f); return (u + 0x7fffu + ((u >> 16) & 1u)) >> 16; }
; #define MFMA16(a_, b_, c_) __builtin_amdgcn_mfma_f32_16x16x32_bf16((a_), (b_), (c_), 0, 0, 0)
; #define WAVE_FENCE() asm volatile("s_waitcnt lgkmcnt(0)" ::: "memory")
; template <bool OUT>
; __device__ __forceinline__ void ssm_fast(KArgs ap, int l, LAS unsigned char* lds, const Ctx cx) {
;     ...
;             for (int t = 0; t < 32; ++t) {
;                 const float br = *(const LAS float*)(BU + (t * 128 + p) * 4), bi = *(const LAS float*)(BU + (t * 128 + 64 + p) * 4);
;                 const float nr = are * sr - aim * si + br, ni = are * si + aim * sr + bi; sr = nr; si = ni;
;                 if (OUT) { asm volatile("" ::: "memory");
;                     *(LAS bf16_t*)(BU + t * 512 + ((((p >> 3)) ^ (t & 15)) << 4) + (p & 7) * 2) = (bf16_t)f2bf(sr);
;                     *(LAS bf16_t*)(BU + t * 512 + (((8 + (p >> 3)) ^ (t & 15)) << 4) + (p & 7) * 2) = (bf16_t)f2bf(si); }
;             }
;             if (OUT) {
;                 WAVE_FENCE();
;                 const int row = lane & 15, kq = lane >> 4;
; #pragma unroll
;                 for (int tbk = 0; tbk < 2; ++tbk) { f32x4 acc = (f32x4){0.f, 0.f, 0.f, 0.f};
; #pragma unroll
;                     for (int ks = 0; ks < 4; ++ks) { const bf16x8 af = *(const LAS bf16x8*)(BU + (tbk * 16 + row) * 512 + (((ks * 4 + kq) ^ row) << 4)); acc = MFMA16(af, ct[ks], acc); }
; #pragma unroll
;                     for (int j = 0; j < 4; ++j) { const size_t tok = tk + tbk * 16 + 4 * kq + j;
;                         const float uval = bf2f(uv[tbk][j]);
;                         ypre[tok * 512 + g * 16 + row] = (bf16_t)f2bf(gelu_tanh(acc[j] + dsk * uval)); } }
;             }
;         }
;         if (!OUT) { E[(size_t)it * 128 + p] = sr; E[(size_t)it * 128 + 64 + p] = si; }
	v_fma_f32 v114, v80, v92, -v113
	v_fma_f32 v116, v81, v92, v115
	v_add_f32_e32 v92, v114, v6
	v_add_f32_e32 v93, v116, v38
	v_mul_f32_e32 v113, v81, v93
	v_mul_f32_e32 v115, v80, v93
	v_fma_f32 v114, v80, v92, -v113
	v_fma_f32 v116, v81, v92, v115
	v_add_f32_e32 v92, v114, v7
	v_add_f32_e32 v93, v116, v39
	v_mul_f32_e32 v113, v81, v93
	v_mul_f32_e32 v115, v80, v93
	v_fma_f32 v114, v80, v92, -v113
	v_fma_f32 v116, v81, v92, v115
	v_add_f32_e32 v92, v114, v20
	v_add_f32_e32 v93, v116, v52
	v_mul_f32_e32 v113, v81, v93
	v_mul_f32_e32 v115, v80, v93
	v_fma_f32 v114, v80, v92, -v113
	v_fma_f32 v116, v81, v92, v115
	v_add_f32_e32 v92, v114, v21
	v_add_f32_e32 v93, v116, v53
	v_mul_f32_e32 v113, v81, v93
	v_mul_f32_e32 v115, v80, v93
	v_fma_f32 v114, v80, v92, -v113
	v_fma_f32 v116, v81, v92, v115
	v_add_f32_e32 v92, v114, v22
	v_add_f32_e32 v93, v116, v54
	v_mul_f32_e32 v113, v81, v93
	v_mul_f32_e32 v115, v80, v93
	v_fma_f32 v114, v80, v92, -v113
	v_fma_f32 v116, v81, v92, v115
	v_add_f32_e32 v92, v114, v23
	v_add_f32_e32 v93, v116, v55
	v_mul_f32_e32 v113, v81, v93
	v_mul_f32_e32 v115, v80, v93
	v_fma_f32 v114, v80, v92, -v113
	v_fma_f32 v116, v81, v92, v115
	v_add_f32_e32 v92, v114, v8
	v_add_f32_e32 v93, v116, v40
	v_mul_f32_e32 v113, v81, v93
	v_mul_f32_e32 v115, v80, v93
	v_fma_f32 v114, v80, v92, -v113
	v_fma_f32 v116, v81, v92, v115
	v_add_f32_e32 v92, v114, v9
	v_add_f32_e32 v93, v116, v41
	v_mul_f32_e32 v113, v81, v93
	v_mul_f32_e32 v115, v80, v93
	v_fma_f32 v114, v80, v92, -v113
	v_fma_f32 v116, v81, v92, v115
	v_add_f32_e32 v92, v114, v10
	v_add_f32_e32 v93, v116, v42
	v_mul_f32_e32 v113, v81, v93
	v_mul_f32_e32 v115, v80, v93
	v_fma_f32 v114, v80, v92, -v113
	v_fma_f32 v116, v81, v92, v115
	v_add_f32_e32 v92, v114, v11
	v_add_f32_e32 v93, v116, v43
	v_mul_f32_e32 v113, v81, v93
	v_mul_f32_e32 v115, v80, v93
	v_fma_f32 v114, v80, v92, -v113
	v_fma_f32 v116, v81, v92, v115
	v_add_f32_e32 v92, v114, v24
	v_add_f32_e32 v93, v116, v56
	v_mul_f32_e32 v113, v81, v93
	v_mul_f32_e32 v115, v80, v93
	v_fma_f32 v114, v80, v92, -v113
	v_fma_f32 v116, v81, v92, v115
	v_add_f32_e32 v92, v114, v25
	v_add_f32_e32 v93, v116, v57
	v_mul_f32_e32 v113, v81, v93
	v_mul_f32_e32 v115, v80, v93
	v_fma_f32 v114, v80, v92, -v113
	v_fma_f32 v116, v81, v92, v115
	v_add_f32_e32 v92, v114, v26
	v_add_f32_e32 v93, v116, v58
	v_mul_f32_e32 v113, v81, v93
	v_mul_f32_e32 v115, v80, v93
	v_fma_f32 v114, v80, v92, -v113
	v_fma_f32 v116, v81, v92, v115
	v_add_f32_e32 v92, v114, v27
	v_add_f32_e32 v93, v116, v59
	v_mul_f32_e32 v113, v81, v93
	v_mul_f32_e32 v115, v80, v93
	v_fma_f32 v114, v80, v92, -v113
	v_fma_f32 v116, v81, v92, v115
	v_add_f32_e32 v92, v114, v12
	v_add_f32_e32 v93, v116, v44
	v_mul_f32_e32 v113, v81, v93
	v_mul_f32_e32 v115, v80, v93
	v_fma_f32 v114, v80, v92, -v113
	v_fma_f32 v116, v81, v92, v115
	v_add_f32_e32 v92, v114, v13
	v_add_f32_e32 v93, v116, v45
	v_mul_f32_e32 v113, v81, v93
	v_mul_f32_e32 v115, v80, v93
	v_fma_f32 v114, v80, v92, -v113
	v_fma_f32 v116, v81, v92, v115
	v_add_f32_e32 v92, v114, v14
	v_add_f32_e32 v93, v116, v46
	v_mul_f32_e32 v113, v81, v93
	v_mul_f32_e32 v115, v80, v93
	v_fma_f32 v114, v80, v92, -v113
	v_fma_f32 v116, v81, v92, v115
	v_add_f32_e32 v92, v114, v15
	v_add_f32_e32 v93, v116, v47
	v_mul_f32_e32 v113, v81, v93
	v_mul_f32_e32 v115, v80, v93
	v_fma_f32 v114, v80, v92, -v113
	v_fma_f32 v116, v81, v92, v115
	v_add_f32_e32 v92, v114, v28
	v_add_f32_e32 v93, v116, v60
	v_mul_f32_e32 v113, v81, v93
	v_mul_f32_e32 v115, v80, v93
	v_fma_f32 v114, v80, v92, -v113
	v_fma_f32 v116, v81, v92, v115
	v_add_f32_e32 v92, v114, v29
	v_add_f32_e32 v93, v116, v61
	v_mul_f32_e32 v113, v81, v93
	v_mul_f32_e32 v115, v80, v93
	v_fma_f32 v114, v80, v92, -v113
	v_fma_f32 v116, v81, v92, v115
	v_add_f32_e32 v92, v114, v30
	v_add_f32_e32 v93, v116, v62
	v_mul_f32_e32 v113, v81, v93
	v_mul_f32_e32 v115, v80, v93
	v_fma_f32 v114, v80, v92, -v113
	v_fma_f32 v116, v81, v92, v115
	v_add_f32_e32 v92, v114, v31
	v_add_f32_e32 v93, v116, v63
	s_add_i32 s5, s5, 1
	s_cmp_eq_u32 s5, 4
	s_cbranch_scc0 .LBB0_170
	s_ashr_i32 s5, s4, 31
	s_lshl_b64 s[10:11], s[4:5], 9
	s_add_i32 s4, s4, s8
	v_lshl_add_u64 v[0:1], v[82:83], 0, s[10:11]
	s_cmpk_gt_i32 s4, 0x1fff
	global_store_dword v[0:1], v92, off
	global_store_dword v[0:1], v93, off offset:256
	s_cbranch_scc0 .LBB0_169

; #define LAS __attribute__((address_space(3)))
; #define a (*get_args())
; template <bool OUT>
; __device__ __forceinline__ void ssm_fast(KArgs ap, int l, LAS unsigned char* lds, const Ctx cx) {
;     ...
;     const bf16_t* z = (const bf16_t*)(a.ws + WS_Z); bf16_t* ypre = (bf16_t*)(a.ws + WS_YPRE); float* E = (float*)(a.ws + WS_E);
;     const unsigned char* tb = a.ws + WS_TAB + (size_t)l * TAB_STRIDE;
;     const int gw = cx.bid * 8 + wave, NGW = cx.nb * 8;
;     const int g = gw & 31, r = lane & 31, hh = lane >> 5, p = lane;
;     LAS unsigned char* BU = lds + wave * 16384;
;     const float are = ((const float*)(tb + TAB_A))[(g * 64 + p) * 2], aim = ((const float*)(tb + TAB_A))[(g * 64 + p) * 2 + 1];
;     bf16x8 bt[4];
; #pragma unroll
;     for (int nb = 0; nb < 4; ++nb) bt[nb] = *(const bf16x8*)((const bf16_t*)(tb + TAB_BT) + (g * 128 + nb * 32 + r) * 16 + 8 * hh);
;     bf16x8 ct[4]; float dsk = 0.f;
;     if (OUT) {
; #pragma unroll
;         for (int ks = 0; ks < 4; ++ks) ct[ks] = *(const bf16x8*)((const bf16_t*)(tb + TAB_CT) + (g * 16 + (lane & 15)) * 128 + ks * 32 + 8 * (lane >> 4));
;         dsk = a.in[I_SSM_D][l * 512 + g * 16 + (lane & 15)];
;     }
;     __syncthreads();
; #pragma unroll 1
;     for (int it = gw; it < BATCH * SSM_NC * 32; it += NGW) {
;         const size_t tok0 = (size_t)(it >> 5) * 128;
;         float sr = 0.f, si = 0.f;
;         if (OUT) { sr = E[(size_t)it * 128 + p]; si = E[(size_t)it * 128 + 64 + p]; }
; #pragma unroll 1
;         for (int sc = 0; sc < 4; ++sc) {
;             const size_t tk = tok0 + sc * 32;
;             const bf16x8 uf = *(const bf16x8*)(z + (tk + r) * DIN + ZS + g * 16 + 8 * hh);
.LBB0_305:
.LBB0_306:
	s_mov_b64 s[0:1], s[78:79]
	s_load_dword s0, s[0:1], 0xe0
	v_readlane_b32 s1, v243, 18
	s_add_i32 s56, s1, 6
	s_waitcnt lgkmcnt(0)
	s_cmp_gt_i32 s0, s55
	s_cbranch_scc1 .LBB0_376
	s_mov_b64 s[0:1], s[78:79]
	s_load_dword s0, s[0:1], 0xe4
	s_waitcnt lgkmcnt(0)
	s_cmp_ge_i32 s55, s0
	s_cbranch_scc1 .LBB0_376
	v_readlane_b32 s4, v243, 5
	v_mov_b32_e32 v8, v192
	v_readlane_b32 s0, v243, 0
	v_readlane_b32 s5, v243, 6
	s_load_dword s6, s[4:5], 0x0
	v_readfirstlane_b32 s1, v8
	s_ashr_i32 s8, s1, 6
	s_lshl_b32 s0, s0, 3
	s_add_i32 s0, s8, s0
	s_waitcnt lgkmcnt(0)
	s_mov_b32 s7, s6
	s_mov_b64 s[10:11], s[78:79]
	v_and_b32_e32 v2, 63, v8
	s_and_b32 s9, s0, 31
	s_load_dwordx2 s[4:5], s[10:11], 0xd8
	v_and_b32_e32 v96, 31, v8
	s_lshl_b32 s1, s9, 7
	v_lshlrev_b32_e32 v3, 1, v2
	v_or_b32_e32 v4, s1, v3
	v_or_b32_e32 v6, s1, v96
	s_lshl_b32 s1, s9, 4
	v_readlane_b32 s12, v243, 21
	s_or_b32 s12, s1, s12
	v_and_b32_e32 v0, 15, v8
	v_or_b32_e32 v152, s12, v0
	v_readlane_b32 s12, v243, 19
	v_readlane_b32 s13, v243, 22
	s_waitcnt lgkmcnt(0)
	s_add_u32 s12, s4, s12
	s_addc_u32 s13, s5, 0
	v_bfe_u32 v1, v8, 5, 1
	s_add_u32 s12, s12, 0x3e600000
	s_addc_u32 s13, s13, 0
	v_lshlrev_b32_e32 v9, 2, v4
	v_lshlrev_b32_e32 v4, 4, v1
	v_mov_b32_e32 v5, v153
	v_lshl_add_u64 v[4:5], s[12:13], 0, v[4:5]
	v_lshlrev_b32_e32 v6, 5, v6
	v_mov_b32_e32 v7, v153
	v_lshl_add_u64 v[4:5], v[4:5], 0, v[6:7]
	s_mov_b64 s[14:15], 0x8000
	v_lshl_add_u64 v[6:7], v[4:5], 0, s[14:15]
	s_load_dwordx2 s[10:11], s[10:11], 0x58
	global_load_dwordx2 v[98:99], v9, s[12:13]
	global_load_dwordx4 v[64:67], v[6:7], off offset:1024
	global_load_dwordx4 v[68:71], v[6:7], off offset:2048
	global_load_dwordx4 v[72:75], v[6:7], off offset:3072
	v_lshlrev_b32_e32 v6, 8, v8
	v_and_b32_e32 v6, 0xf00, v6
	s_mov_b32 s14, 0x8000
	v_lshl_or_b32 v6, s9, 12, v6
	v_mov_b32_e32 v7, v153
	v_add_co_u32_e32 v4, vcc, s14, v4
	v_lshl_add_u64 v[6:7], s[12:13], 0, v[6:7]
	v_and_b32_e32 v8, 48, v8
	v_mov_b32_e32 v9, v153
	v_addc_co_u32_e32 v5, vcc, 0, v5, vcc
	v_lshl_add_u64 v[6:7], v[6:7], 0, v[8:9]
	s_mov_b64 s[12:13], 0x28000
	v_lshl_add_u64 v[8:9], v[6:7], 0, s[12:13]
	v_add_co_u32_e32 v6, vcc, 0x28000, v6
	s_cmpk_gt_i32 s0, 0x1fff
	s_nop 0
	v_addc_co_u32_e32 v7, vcc, 0, v7, vcc
	global_load_dwordx4 v[76:79], v[6:7], off
	global_load_dwordx4 v[80:83], v[4:5], off
	global_load_dwordx4 v[84:87], v[8:9], off offset:64
	global_load_dwordx4 v[88:91], v[8:9], off offset:128
	global_load_dwordx4 v[92:95], v[8:9], off offset:192
	s_waitcnt lgkmcnt(0)
	v_lshl_add_u64 v[4:5], v[152:153], 2, s[10:11]
	global_load_dword v97, v[4:5], off
	s_waitcnt vmcnt(0)
	s_barrier
	s_cbranch_scc1 .LBB0_315
	s_lshl_b32 s8, s8, 14
	v_lshlrev_b32_e32 v4, 3, v1
	s_add_i32 s10, s8, 0
	v_lshrrev_b32_e32 v5, 2, v2
	v_lshlrev_b32_e32 v152, 2, v2
	v_lshrrev_b32_e32 v103, 3, v2
	v_and_b32_e32 v6, 14, v3
	v_lshrrev_b32_e32 v2, 4, v2
	v_lshlrev_b32_e32 v1, 11, v1
	v_lshlrev_b32_e32 v3, 2, v96
	v_add3_u32 v107, s10, v1, v3
	v_xor_b32_e32 v1, v2, v0
	v_and_b32_e32 v100, 12, v5
	v_or_b32_e32 v110, 3, v5
	v_or_b32_e32 v118, 19, v5
	v_lshlrev_b32_e32 v5, 4, v1
	v_bitop3_b32 v1, v2, v0, 4 bitop3:0x36
	v_lshlrev_b32_e32 v8, 4, v1
	v_bitop3_b32 v1, v2, v0, 8 bitop3:0x36
	s_lshl_b32 s7, s7, 3
	v_lshlrev_b32_e32 v102, 2, v2
	v_lshlrev_b32_e32 v9, 4, v1
	v_bitop3_b32 v1, v2, v0, 12 bitop3:0x36
	v_lshl_add_u64 v[2:3], s[4:5], 0, v[152:153]
	s_mov_b64 s[8:9], 0x3e000000
	s_lshl_b32 s1, s1, 1
	v_lshl_add_u64 v[132:133], v[2:3], 0, s[8:9]
	s_add_u32 s8, s4, s1
	s_addc_u32 s9, s5, 0
	s_add_u32 s1, s4, s1
	v_add_u32_e32 v101, s10, v152
	v_lshlrev_b32_e32 v152, 1, v0
	s_addc_u32 s5, s5, 0
	v_lshl_add_u32 v7, v0, 9, s10
	v_lshlrev_b32_e32 v10, 4, v1
	v_lshl_add_u64 v[0:1], s[8:9], 0, v[152:153]
	s_mov_b64 s[8:9], 0x3c000000
	s_add_u32 s4, s1, 0x13000000
	v_lshl_add_u64 v[134:135], v[0:1], 0, s[8:9]
	s_addc_u32 s5, s5, 0
	v_lshlrev_b32_e32 v0, 1, v4
	v_mov_b32_e32 v1, v153
	v_or_b32_e32 v105, 8, v103
	v_or_b32_e32 v104, 16, v102
	v_or_b32_e32 v106, 1, v100
	v_or_b32_e32 v108, 2, v100
	v_or_b32_e32 v112, 16, v100
	v_or_b32_e32 v114, 17, v100
	v_or_b32_e32 v116, 18, v100
	v_or_b32_e32 v120, 1, v102
	v_or_b32_e32 v122, 2, v102
	v_or_b32_e32 v124, 3, v102
	v_or_b32_e32 v126, 17, v102
	v_or_b32_e32 v128, 18, v102
	v_or_b32_e32 v130, 19, v102
	v_pk_mov_b32 v[136:137], v[98:99], v[98:99] op_sel:[1,0]
	v_lshl_add_u64 v[138:139], s[4:5], 0, v[0:1]
	v_lshl_add_u64 v[140:141], s[4:5], 0, v[152:153]
	v_add_u32_e32 v109, s10, v6
	v_add_u32_e32 v111, v7, v5
	v_add_u32_e32 v113, v7, v8
	v_add_u32_e32 v115, v7, v9
	v_add_u32_e32 v117, v7, v10
	s_mov_b32 s58, 0x2c000
	s_mov_b32 s59, 0
	v_xor_b32_e32 v215, 0, v103
	v_lshl_add_u32 v199, v215, 4, v109
	v_xor_b32_e32 v215, 1, v103
	v_lshl_add_u32 v200, v215, 4, v109
	v_xor_b32_e32 v215, 2, v103
	v_lshl_add_u32 v201, v215, 4, v109
	v_xor_b32_e32 v215, 3, v103
	v_lshl_add_u32 v202, v215, 4, v109
	v_xor_b32_e32 v215, 4, v103
	v_lshl_add_u32 v203, v215, 4, v109
	v_xor_b32_e32 v215, 5, v103
	v_lshl_add_u32 v204, v215, 4, v109
	v_xor_b32_e32 v215, 6, v103
	v_lshl_add_u32 v205, v215, 4, v109
	v_xor_b32_e32 v215, 7, v103
	v_lshl_add_u32 v206, v215, 4, v109
	v_xor_b32_e32 v215, 8, v103
	v_lshl_add_u32 v207, v215, 4, v109
	v_xor_b32_e32 v215, 9, v103
	v_lshl_add_u32 v208, v215, 4, v109
	v_xor_b32_e32 v215, 10, v103
	v_lshl_add_u32 v209, v215, 4, v109
	v_xor_b32_e32 v215, 11, v103
	v_lshl_add_u32 v210, v215, 4, v109
	v_xor_b32_e32 v215, 12, v103
	v_lshl_add_u32 v211, v215, 4, v109
	v_xor_b32_e32 v215, 13, v103
	v_lshl_add_u32 v212, v215, 4, v109
	v_xor_b32_e32 v215, 14, v103
	v_lshl_add_u32 v213, v215, 4, v109
	v_xor_b32_e32 v215, 15, v103
	v_lshl_add_u32 v214, v215, 4, v109

; #define LAS __attribute__((address_space(3)))
; __device__ __forceinline__ unsigned f2bf(float f) { unsigned u = __builtin_bit_cast(unsigned, f); return (u + 0x7fffu + ((u >> 16) & 1u)) >> 16; }
; #define MFMA32(a_, b_, c_) __builtin_amdgcn_mfma_f32_32x32x16_bf16((a_), (b_), (c_), 0, 0, 0)
; __device__ __forceinline__ int crow(int reg, int h) { return (reg & 3) + 8 * (reg >> 2) + 4 * h; }
; #define WAVE_FENCE() asm volatile("s_waitcnt lgkmcnt(0)" ::: "memory")
; template <bool OUT>
; __device__ __forceinline__ void ssm_fast(KArgs ap, int l, LAS unsigned char* lds, const Ctx cx) {
;     ...
;         for (int sc = 0; sc < 4; ++sc) {
;             const size_t tk = tok0 + sc * 32;
;             const bf16x8 uf = *(const bf16x8*)(z + (tk + r) * DIN + ZS + g * 16 + 8 * hh);
;             bf16_t uv[2][4];
;             if (OUT) {
; #pragma unroll
;                 for (int tbk = 0; tbk < 2; ++tbk)
; #pragma unroll
;                     for (int j = 0; j < 4; ++j) uv[tbk][j] = z[(tk + tbk * 16 + 4 * (lane >> 4) + j) * DIN + ZS + g * 16 + (lane & 15)];
;             }
;             WAVE_FENCE();
; #pragma unroll
;             for (int nb = 0; nb < 4; ++nb) { f32x16 c;
; #pragma unroll
;                 for (int i = 0; i < 16; ++i) c[i] = 0.f;
;                 c = MFMA32(uf, bt[nb], c);
; #pragma unroll
;                 for (int i = 0; i < 16; ++i) *(LAS float*)(BU + (crow(i, hh) * 128 + nb * 32 + r) * 4) = c[i]; }
;             WAVE_FENCE();
; #pragma unroll 4
;             for (int t = 0; t < 32; ++t) {
;                 const float br = *(const LAS float*)(BU + (t * 128 + p) * 4), bi = *(const LAS float*)(BU + (t * 128 + 64 + p) * 4);
;                 const float nr = are * sr - aim * si + br, ni = are * si + aim * sr + bi; sr = nr; si = ni;
;                 if (OUT) { asm volatile("" ::: "memory");
;                     *(LAS bf16_t*)(BU + t * 512 + ((((p >> 3)) ^ (t & 15)) << 4) + (p & 7) * 2) = (bf16_t)f2bf(sr);
;                     *(LAS bf16_t*)(BU + t * 512 + (((8 + (p >> 3)) ^ (t & 15)) << 4) + (p & 7) * 2) = (bf16_t)f2bf(si); }
.LBB0_311:
	s_lshl_b32 s8, s1, 5
	s_add_u32 s8, s4, s8
	v_or_b32_e32 v0, s8, v96
	s_movk_i32 s12, 0x1600
	s_addc_u32 s9, s5, 0
	v_mad_u64_u32 v[0:1], s[10:11], v0, s12, v[138:139]
	v_mad_i32_i24 v1, s9, v198, v1
	s_cmp_lg_u32 s1, 0
	s_cbranch_scc1 .Lssmc_have_u
	global_load_dwordx4 v[170:173], v[0:1], off offset:2560
.Lssmc_have_u:
	v_lshl_add_u64 v[174:175], v[0:1], 0, s[58:59]
	v_or_b32_e32 v0, s8, v100
	v_or_b32_e32 v1, s8, v106
	v_or_b32_e32 v2, s8, v108
	v_or_b32_e32 v3, s8, v110
	v_or_b32_e32 v4, s8, v112
	v_or_b32_e32 v5, s8, v114
	v_or_b32_e32 v6, s8, v116
	v_or_b32_e32 v7, s8, v118
	v_mad_u64_u32 v[32:33], s[10:11], v0, s12, v[140:141]
	v_mad_u64_u32 v[34:35], s[10:11], v1, s12, v[140:141]
	v_mad_u64_u32 v[36:37], s[10:11], v2, s12, v[140:141]
	v_mad_u64_u32 v[38:39], s[10:11], v3, s12, v[140:141]
	v_mad_u64_u32 v[40:41], s[10:11], v4, s12, v[140:141]
	v_mad_u64_u32 v[42:43], s[10:11], v5, s12, v[140:141]
	v_mad_u64_u32 v[44:45], s[10:11], v6, s12, v[140:141]
	v_mad_u64_u32 v[46:47], s[10:11], v7, s12, v[140:141]
	v_mad_i32_i24 v33, s9, v198, v33
	v_mad_i32_i24 v35, s9, v198, v35
	v_mad_i32_i24 v37, s9, v198, v37
	v_mad_i32_i24 v39, s9, v198, v39
	v_mad_i32_i24 v41, s9, v198, v41
	v_mad_i32_i24 v43, s9, v198, v43
	v_mad_i32_i24 v45, s9, v198, v45
	v_mad_i32_i24 v47, s9, v198, v47
	global_load_ushort v144, v[32:33], off offset:2560
	global_load_ushort v131, v[34:35], off offset:2560
	global_load_ushort v129, v[36:37], off offset:2560
	global_load_ushort v127, v[38:39], off offset:2560
	global_load_ushort v125, v[40:41], off offset:2560
	global_load_ushort v123, v[42:43], off offset:2560
	global_load_ushort v121, v[44:45], off offset:2560
	global_load_ushort v119, v[46:47], off offset:2560
	v_add_u32_e32 v145, 0x400, v107
	v_add_u32_e32 v146, 0x1000, v107
	v_add_u32_e32 v147, 0x1400, v107
	v_add_u32_e32 v148, 0x2000, v107
	v_add_u32_e32 v149, 0x2400, v107
	v_add_u32_e32 v150, 0x3000, v107
	v_add_u32_e32 v151, 0x3400, v107
	s_waitcnt lgkmcnt(0)
	s_movk_i32 s10, 0xc000
	s_mov_b32 s11, 3
	s_waitcnt vmcnt(8)
	v_mfma_f32_32x32x16_bf16 v[0:15], v[170:173], v[80:83], 0
	v_mfma_f32_32x32x16_bf16 v[16:31], v[170:173], v[64:67], 0
	v_mfma_f32_32x32x16_bf16 v[32:47], v[170:173], v[68:71], 0
	v_mfma_f32_32x32x16_bf16 v[48:63], v[170:173], v[72:75], 0
	s_nop 9
	s_cmp_eq_u32 s1, 3
	s_cbranch_scc1 .Lssmc_no_pf
	global_load_dwordx4 v[170:173], v[174:175], off offset:2560
.Lssmc_no_pf:
	s_waitcnt lgkmcnt(0)
.LBB0_312:
	v_permlane32_swap_b32_e32 v0, v16
	v_permlane32_swap_b32_e32 v1, v17
	v_permlane32_swap_b32_e32 v2, v18
	v_permlane32_swap_b32_e32 v3, v19
	v_permlane32_swap_b32_e32 v4, v20
	v_permlane32_swap_b32_e32 v5, v21
	v_permlane32_swap_b32_e32 v6, v22
	v_permlane32_swap_b32_e32 v7, v23
	v_permlane32_swap_b32_e32 v8, v24
	v_permlane32_swap_b32_e32 v9, v25
	v_permlane32_swap_b32_e32 v10, v26
	v_permlane32_swap_b32_e32 v11, v27
	v_permlane32_swap_b32_e32 v12, v28
	v_permlane32_swap_b32_e32 v13, v29
	v_permlane32_swap_b32_e32 v14, v30
	v_permlane32_swap_b32_e32 v15, v31
	v_permlane32_swap_b32_e32 v32, v48
	v_permlane32_swap_b32_e32 v33, v49
	v_permlane32_swap_b32_e32 v34, v50
	v_permlane32_swap_b32_e32 v35, v51
	v_permlane32_swap_b32_e32 v36, v52
	v_permlane32_swap_b32_e32 v37, v53
	v_permlane32_swap_b32_e32 v38, v54
	v_permlane32_swap_b32_e32 v39, v55
	v_permlane32_swap_b32_e32 v40, v56
	v_permlane32_swap_b32_e32 v41, v57
	v_permlane32_swap_b32_e32 v42, v58
	v_permlane32_swap_b32_e32 v43, v59
	v_permlane32_swap_b32_e32 v44, v60
	v_permlane32_swap_b32_e32 v45, v61
	v_permlane32_swap_b32_e32 v46, v62
	v_permlane32_swap_b32_e32 v47, v63
	v_mul_f32_e32 v176, v99, v143
	v_mul_f32_e32 v178, v98, v143
	v_fma_f32 v177, v98, v142, -v176
	v_fma_f32 v179, v99, v142, v178
	v_add_f32_e32 v142, v177, v0
	v_add_f32_e32 v143, v179, v32
	v_cvt_pk_bf16_f32 v184, v142, v143
	ds_write_b16 v199, v184 offset:0
	ds_write_b16_d16_hi v207, v184 offset:0
	v_mul_f32_e32 v176, v99, v143
	v_mul_f32_e32 v178, v98, v143
	v_fma_f32 v177, v98, v142, -v176
	v_fma_f32 v179, v99, v142, v178
	v_add_f32_e32 v142, v177, v1
	v_add_f32_e32 v143, v179, v33
	v_cvt_pk_bf16_f32 v185, v142, v143
	ds_write_b16 v200, v185 offset:512
	ds_write_b16_d16_hi v208, v185 offset:512
	v_mul_f32_e32 v176, v99, v143
	v_mul_f32_e32 v178, v98, v143
	v_fma_f32 v177, v98, v142, -v176
	v_fma_f32 v179, v99, v142, v178
	v_add_f32_e32 v142, v177, v2
	v_add_f32_e32 v143, v179, v34
	v_cvt_pk_bf16_f32 v186, v142, v143
	ds_write_b16 v201, v186 offset:1024
	ds_write_b16_d16_hi v209, v186 offset:1024
	v_mul_f32_e32 v176, v99, v143
	v_mul_f32_e32 v178, v98, v143
	v_fma_f32 v177, v98, v142, -v176
	v_fma_f32 v179, v99, v142, v178
	v_add_f32_e32 v142, v177, v3
	v_add_f32_e32 v143, v179, v35
	v_cvt_pk_bf16_f32 v187, v142, v143
	ds_write_b16 v202, v187 offset:1536
	ds_write_b16_d16_hi v210, v187 offset:1536
	v_mul_f32_e32 v176, v99, v143
	v_mul_f32_e32 v178, v98, v143
	v_fma_f32 v177, v98, v142, -v176
	v_fma_f32 v179, v99, v142, v178
	v_add_f32_e32 v142, v177, v16
	v_add_f32_e32 v143, v179, v48
	v_cvt_pk_bf16_f32 v184, v142, v143
	ds_write_b16 v203, v184 offset:2048
	ds_write_b16_d16_hi v211, v184 offset:2048
	v_mul_f32_e32 v176, v99, v143
	v_mul_f32_e32 v178, v98, v143
	v_fma_f32 v177, v98, v142, -v176
	v_fma_f32 v179, v99, v142, v178
	v_add_f32_e32 v142, v177, v17
	v_add_f32_e32 v143, v179, v49
	v_cvt_pk_bf16_f32 v185, v142, v143
	ds_write_b16 v204, v185 offset:2560
	ds_write_b16_d16_hi v212, v185 offset:2560
	v_mul_f32_e32 v176, v99, v143
	v_mul_f32_e32 v178, v98, v143
	v_fma_f32 v177, v98, v142, -v176
	v_fma_f32 v179, v99, v142, v178
	v_add_f32_e32 v142, v177, v18
	v_add_f32_e32 v143, v179, v50
	v_cvt_pk_bf16_f32 v186, v142, v143
; #define LAS __attribute__((address_space(3)))
; __device__ __forceinline__ unsigned f2bf(float f) { unsigned u = __builtin_bit_cast(unsigned, f); return (u + 0x7fffu + ((u >> 16) & 1u)) >> 16; }
; template <bool OUT>
; __device__ __forceinline__ void ssm_fast(KArgs ap, int l, LAS unsigned char* lds, const Ctx cx) {
;     ...
;             for (int t = 0; t < 32; ++t) {
;                 const float br = *(const LAS float*)(BU + (t * 128 + p) * 4), bi = *(const LAS float*)(BU + (t * 128 + 64 + p) * 4);
;                 const float nr = are * sr - aim * si + br, ni = are * si + aim * sr + bi; sr = nr; si = ni;
;                 if (OUT) { asm volatile("" ::: "memory");
;                     *(LAS bf16_t*)(BU + t * 512 + ((((p >> 3)) ^ (t & 15)) << 4) + (p & 7) * 2) = (bf16_t)f2bf(sr);
;                     *(LAS bf16_t*)(BU + t * 512 + (((8 + (p >> 3)) ^ (t & 15)) << 4) + (p & 7) * 2) = (bf16_t)f2bf(si); }
	ds_write_b16 v205, v186 offset:3072
	ds_write_b16_d16_hi v213, v186 offset:3072
	v_mul_f32_e32 v176, v99, v143
	v_mul_f32_e32 v178, v98, v143
	v_fma_f32 v177, v98, v142, -v176
	v_fma_f32 v179, v99, v142, v178
	v_add_f32_e32 v142, v177, v19
	v_add_f32_e32 v143, v179, v51
	v_cvt_pk_bf16_f32 v187, v142, v143
	ds_write_b16 v206, v187 offset:3584
	ds_write_b16_d16_hi v214, v187 offset:3584
	v_mul_f32_e32 v176, v99, v143
	v_mul_f32_e32 v178, v98, v143
	v_fma_f32 v177, v98, v142, -v176
	v_fma_f32 v179, v99, v142, v178
	v_add_f32_e32 v142, v177, v4
	v_add_f32_e32 v143, v179, v36
	v_cvt_pk_bf16_f32 v184, v142, v143
	ds_write_b16 v207, v184 offset:4096
	ds_write_b16_d16_hi v199, v184 offset:4096
	v_mul_f32_e32 v176, v99, v143
	v_mul_f32_e32 v178, v98, v143
	v_fma_f32 v177, v98, v142, -v176
	v_fma_f32 v179, v99, v142, v178
	v_add_f32_e32 v142, v177, v5
	v_add_f32_e32 v143, v179, v37
	v_cvt_pk_bf16_f32 v185, v142, v143
	ds_write_b16 v208, v185 offset:4608
	ds_write_b16_d16_hi v200, v185 offset:4608
	v_mul_f32_e32 v176, v99, v143
	v_mul_f32_e32 v178, v98, v143
	v_fma_f32 v177, v98, v142, -v176
	v_fma_f32 v179, v99, v142, v178
	v_add_f32_e32 v142, v177, v6
	v_add_f32_e32 v143, v179, v38
	v_cvt_pk_bf16_f32 v186, v142, v143
	ds_write_b16 v209, v186 offset:5120
	ds_write_b16_d16_hi v201, v186 offset:5120
	v_mul_f32_e32 v176, v99, v143
	v_mul_f32_e32 v178, v98, v143
	v_fma_f32 v177, v98, v142, -v176
	v_fma_f32 v179, v99, v142, v178
	v_add_f32_e32 v142, v177, v7
	v_add_f32_e32 v143, v179, v39
	v_cvt_pk_bf16_f32 v187, v142, v143
	ds_write_b16 v210, v187 offset:5632
	ds_write_b16_d16_hi v202, v187 offset:5632
	v_mul_f32_e32 v176, v99, v143
	v_mul_f32_e32 v178, v98, v143
	v_fma_f32 v177, v98, v142, -v176
	v_fma_f32 v179, v99, v142, v178
	v_add_f32_e32 v142, v177, v20
	v_add_f32_e32 v143, v179, v52
	v_cvt_pk_bf16_f32 v184, v142, v143
	ds_write_b16 v211, v184 offset:6144
	ds_write_b16_d16_hi v203, v184 offset:6144
	v_mul_f32_e32 v176, v99, v143
	v_mul_f32_e32 v178, v98, v143
	v_fma_f32 v177, v98, v142, -v176
	v_fma_f32 v179, v99, v142, v178
	v_add_f32_e32 v142, v177, v21
	v_add_f32_e32 v143, v179, v53
	v_cvt_pk_bf16_f32 v185, v142, v143
	ds_write_b16 v212, v185 offset:6656
	ds_write_b16_d16_hi v204, v185 offset:6656
	v_mul_f32_e32 v176, v99, v143
	v_mul_f32_e32 v178, v98, v143
	v_fma_f32 v177, v98, v142, -v176
	v_fma_f32 v179, v99, v142, v178
	v_add_f32_e32 v142, v177, v22
	v_add_f32_e32 v143, v179, v54
	v_cvt_pk_bf16_f32 v186, v142, v143
	ds_write_b16 v213, v186 offset:7168
	ds_write_b16_d16_hi v205, v186 offset:7168
	v_mul_f32_e32 v176, v99, v143
	v_mul_f32_e32 v178, v98, v143
	v_fma_f32 v177, v98, v142, -v176
	v_fma_f32 v179, v99, v142, v178
	v_add_f32_e32 v142, v177, v23
	v_add_f32_e32 v143, v179, v55
	v_cvt_pk_bf16_f32 v187, v142, v143
	ds_write_b16 v214, v187 offset:7680
	ds_write_b16_d16_hi v206, v187 offset:7680
	v_mul_f32_e32 v176, v99, v143
	v_mul_f32_e32 v178, v98, v143
	v_fma_f32 v177, v98, v142, -v176
	v_fma_f32 v179, v99, v142, v178
	v_add_f32_e32 v142, v177, v8
	v_add_f32_e32 v143, v179, v40
	v_cvt_pk_bf16_f32 v184, v142, v143
	ds_write_b16 v199, v184 offset:8192
	ds_write_b16_d16_hi v207, v184 offset:8192
	v_mul_f32_e32 v176, v99, v143
	v_mul_f32_e32 v178, v98, v143
	v_fma_f32 v177, v98, v142, -v176
	v_fma_f32 v179, v99, v142, v178
	v_add_f32_e32 v142, v177, v9
	v_add_f32_e32 v143, v179, v41
	v_cvt_pk_bf16_f32 v185, v142, v143
	ds_write_b16 v200, v185 offset:8704
	ds_write_b16_d16_hi v208, v185 offset:8704
	v_mul_f32_e32 v176, v99, v143
	v_mul_f32_e32 v178, v98, v143
	v_fma_f32 v177, v98, v142, -v176
	v_fma_f32 v179, v99, v142, v178
	v_add_f32_e32 v142, v177, v10
	v_add_f32_e32 v143, v179, v42
	v_cvt_pk_bf16_f32 v186, v142, v143
	ds_write_b16 v201, v186 offset:9216
	ds_write_b16_d16_hi v209, v186 offset:9216
	v_mul_f32_e32 v176, v99, v143
	v_mul_f32_e32 v178, v98, v143
	v_fma_f32 v177, v98, v142, -v176
	v_fma_f32 v179, v99, v142, v178
	v_add_f32_e32 v142, v177, v11
	v_add_f32_e32 v143, v179, v43
	v_cvt_pk_bf16_f32 v187, v142, v143
	ds_write_b16 v202, v187 offset:9728
	ds_write_b16_d16_hi v210, v187 offset:9728
	v_mul_f32_e32 v176, v99, v143
	v_mul_f32_e32 v178, v98, v143
	v_fma_f32 v177, v98, v142, -v176
	v_fma_f32 v179, v99, v142, v178
	v_add_f32_e32 v142, v177, v24
	v_add_f32_e32 v143, v179, v56
	v_cvt_pk_bf16_f32 v184, v142, v143
	ds_write_b16 v203, v184 offset:10240
	ds_write_b16_d16_hi v211, v184 offset:10240
	v_mul_f32_e32 v176, v99, v143
	v_mul_f32_e32 v178, v98, v143
	v_fma_f32 v177, v98, v142, -v176
	v_fma_f32 v179, v99, v142, v178
	v_add_f32_e32 v142, v177, v25
	v_add_f32_e32 v143, v179, v57
	v_cvt_pk_bf16_f32 v185, v142, v143
	ds_write_b16 v204, v185 offset:10752
	ds_write_b16_d16_hi v212, v185 offset:10752
	v_mul_f32_e32 v176, v99, v143
	v_mul_f32_e32 v178, v98, v143
	v_fma_f32 v177, v98, v142, -v176
	v_fma_f32 v179, v99, v142, v178
	v_add_f32_e32 v142, v177, v26
	v_add_f32_e32 v143, v179, v58
	v_cvt_pk_bf16_f32 v186, v142, v143
	ds_write_b16 v205, v186 offset:11264
	ds_write_b16_d16_hi v213, v186 offset:11264
	v_mul_f32_e32 v176, v99, v143
	v_mul_f32_e32 v178, v98, v143
	v_fma_f32 v177, v98, v142, -v176
	v_fma_f32 v179, v99, v142, v178
	v_add_f32_e32 v142, v177, v27
	v_add_f32_e32 v143, v179, v59
	v_cvt_pk_bf16_f32 v187, v142, v143
	ds_write_b16 v206, v187 offset:11776
	ds_write_b16_d16_hi v214, v187 offset:11776
	v_mul_f32_e32 v176, v99, v143
	v_mul_f32_e32 v178, v98, v143
	v_fma_f32 v177, v98, v142, -v176
	v_fma_f32 v179, v99, v142, v178
	v_add_f32_e32 v142, v177, v12
	v_add_f32_e32 v143, v179, v44
	v_cvt_pk_bf16_f32 v184, v142, v143
	ds_write_b16 v207, v184 offset:12288
	ds_write_b16_d16_hi v199, v184 offset:12288
; #define LAS __attribute__((address_space(3)))
; __device__ __forceinline__ unsigned f2bf(float f) { unsigned u = __builtin_bit_cast(unsigned, f); return (u + 0x7fffu + ((u >> 16) & 1u)) >> 16; }
; #define MFMA16(a_, b_, c_) __builtin_amdgcn_mfma_f32_16x16x32_bf16((a_), (b_), (c_), 0, 0, 0)
; #define WAVE_FENCE() asm volatile("s_waitcnt lgkmcnt(0)" ::: "memory")
; template <bool OUT>
; __device__ __forceinline__ void ssm_fast(KArgs ap, int l, LAS unsigned char* lds, const Ctx cx) {
;     ...
;             for (int t = 0; t < 32; ++t) {
;                 const float br = *(const LAS float*)(BU + (t * 128 + p) * 4), bi = *(const LAS float*)(BU + (t * 128 + 64 + p) * 4);
;                 const float nr = are * sr - aim * si + br, ni = are * si + aim * sr + bi; sr = nr; si = ni;
;                 if (OUT) { asm volatile("" ::: "memory");
;                     *(LAS bf16_t*)(BU + t * 512 + ((((p >> 3)) ^ (t & 15)) << 4) + (p & 7) * 2) = (bf16_t)f2bf(sr);
;                     *(LAS bf16_t*)(BU + t * 512 + (((8 + (p >> 3)) ^ (t & 15)) << 4) + (p & 7) * 2) = (bf16_t)f2bf(si); }
;             }
;             if (OUT) {
;                 WAVE_FENCE();
;                 const int row = lane & 15, kq = lane >> 4;
; #pragma unroll
;                 for (int tbk = 0; tbk < 2; ++tbk) { f32x4 acc = (f32x4){0.f, 0.f, 0.f, 0.f};
; #pragma unroll
;                     for (int ks = 0; ks < 4; ++ks) { const bf16x8 af = *(const LAS bf16x8*)(BU + (tbk * 16 + row) * 512 + (((ks * 4 + kq) ^ row) << 4)); acc = MFMA16(af, ct[ks], acc); }
; #pragma unroll
;                     for (int j = 0; j < 4; ++j) { const size_t tok = tk + tbk * 16 + 4 * kq + j;
;                         const float uval = bf2f(uv[tbk][j]);
;                         ypre[tok * 512 + g * 16 + row] = (bf16_t)f2bf(gelu_tanh(acc[j] + dsk * uval)); } }
	v_mul_f32_e32 v176, v99, v143
	v_mul_f32_e32 v178, v98, v143
	v_fma_f32 v177, v98, v142, -v176
	v_fma_f32 v179, v99, v142, v178
	v_add_f32_e32 v142, v177, v13
	v_add_f32_e32 v143, v179, v45
	v_cvt_pk_bf16_f32 v185, v142, v143
	ds_write_b16 v208, v185 offset:12800
	ds_write_b16_d16_hi v200, v185 offset:12800
	v_mul_f32_e32 v176, v99, v143
	v_mul_f32_e32 v178, v98, v143
	v_fma_f32 v177, v98, v142, -v176
	v_fma_f32 v179, v99, v142, v178
	v_add_f32_e32 v142, v177, v14
	v_add_f32_e32 v143, v179, v46
	v_cvt_pk_bf16_f32 v186, v142, v143
	ds_write_b16 v209, v186 offset:13312
	ds_write_b16_d16_hi v201, v186 offset:13312
	v_mul_f32_e32 v176, v99, v143
	v_mul_f32_e32 v178, v98, v143
	v_fma_f32 v177, v98, v142, -v176
	v_fma_f32 v179, v99, v142, v178
	v_add_f32_e32 v142, v177, v15
	v_add_f32_e32 v143, v179, v47
	v_cvt_pk_bf16_f32 v187, v142, v143
	ds_write_b16 v210, v187 offset:13824
	ds_write_b16_d16_hi v202, v187 offset:13824
	v_mul_f32_e32 v176, v99, v143
	v_mul_f32_e32 v178, v98, v143
	v_fma_f32 v177, v98, v142, -v176
	v_fma_f32 v179, v99, v142, v178
	v_add_f32_e32 v142, v177, v28
	v_add_f32_e32 v143, v179, v60
	v_cvt_pk_bf16_f32 v184, v142, v143
	ds_write_b16 v211, v184 offset:14336
	ds_write_b16_d16_hi v203, v184 offset:14336
	v_mul_f32_e32 v176, v99, v143
	v_mul_f32_e32 v178, v98, v143
	v_fma_f32 v177, v98, v142, -v176
	v_fma_f32 v179, v99, v142, v178
	v_add_f32_e32 v142, v177, v29
	v_add_f32_e32 v143, v179, v61
	v_cvt_pk_bf16_f32 v185, v142, v143
	ds_write_b16 v212, v185 offset:14848
	ds_write_b16_d16_hi v204, v185 offset:14848
	v_mul_f32_e32 v176, v99, v143
	v_mul_f32_e32 v178, v98, v143
	v_fma_f32 v177, v98, v142, -v176
	v_fma_f32 v179, v99, v142, v178
	v_add_f32_e32 v142, v177, v30
	v_add_f32_e32 v143, v179, v62
	v_cvt_pk_bf16_f32 v186, v142, v143
	ds_write_b16 v213, v186 offset:15360
	ds_write_b16_d16_hi v205, v186 offset:15360
	v_mul_f32_e32 v176, v99, v143
	v_mul_f32_e32 v178, v98, v143
	v_fma_f32 v177, v98, v142, -v176
	v_fma_f32 v179, v99, v142, v178
	v_add_f32_e32 v142, v177, v31
	v_add_f32_e32 v143, v179, v63
	v_cvt_pk_bf16_f32 v187, v142, v143
	ds_write_b16 v214, v187 offset:15872
	ds_write_b16_d16_hi v206, v187 offset:15872
	s_waitcnt lgkmcnt(0)
	ds_read_b128 v[0:3], v111
	ds_read_b128 v[8:11], v113
	ds_read_b128 v[4:7], v115
	ds_read_b128 v[14:17], v111 offset:8192
	ds_read_b128 v[18:21], v117
	ds_read_b128 v[22:25], v113 offset:8192
	s_waitcnt vmcnt(7)
	v_lshlrev_b32_e32 v28, 16, v144
	v_mov_b32_e32 v13, s9
	v_or_b32_e32 v12, s8, v102
	v_lshlrev_b64 v[12:13], 10, v[12:13]
	v_lshl_add_u64 v[12:13], v[134:135], 0, v[12:13]
	s_waitcnt lgkmcnt(5)
	v_mfma_f32_16x16x32_bf16 v[0:3], v[0:3], v[76:79], 0
	s_waitcnt vmcnt(6)
	v_lshlrev_b32_e32 v29, 16, v131
	v_mov_b32_e32 v27, s9
	v_or_b32_e32 v26, s8, v120
	s_waitcnt lgkmcnt(4)
	v_mfma_f32_16x16x32_bf16 v[0:3], v[8:11], v[84:87], v[0:3]
	ds_read_b128 v[8:11], v115 offset:8192
	s_add_i32 s1, s1, 1
	s_cmp_eq_u32 s1, 4
	s_waitcnt lgkmcnt(4)
	v_mfma_f32_16x16x32_bf16 v[0:3], v[4:7], v[88:91], v[0:3]
	ds_read_b128 v[4:7], v117 offset:8192
	s_waitcnt lgkmcnt(3)
	v_mfma_f32_16x16x32_bf16 v[0:3], v[18:21], v[92:95], v[0:3]
	s_nop 7
	v_fma_f32 v0, v97, v28, v0
	v_mul_f32_e32 v18, 0x3d372713, v0
	v_mul_f32_e32 v18, v0, v18
	v_fma_f32 v18, v0, v18, v0
	v_mul_f32_e32 v18, 0x3f4c422a, v18
	v_add_f32_e32 v18, v18, v18
	v_mul_f32_e32 v18, 0x3fb8aa3b, v18
	v_exp_f32_e32 v18, v18
	v_mul_f32_e32 v0, 0.5, v0
	v_fma_f32 v1, v97, v29, v1
	v_mul_f32_e32 v19, 0x3d372713, v1
	v_add_f32_e32 v18, 1.0, v18
	v_rcp_f32_e32 v18, v18
	v_mul_f32_e32 v19, v1, v19
	v_fma_f32 v19, v1, v19, v1
	v_mul_f32_e32 v19, 0x3f4c422a, v19
	v_fma_f32 v18, v18, -2.0, 1.0
	v_add_f32_e32 v18, 1.0, v18
	v_mul_f32_e32 v0, v0, v18
	v_bfe_u32 v18, v0, 16, 1
	v_add3_u32 v0, v0, v18, s45
	global_store_short_d16_hi v[12:13], v0, off
	s_waitcnt vmcnt(6)
	v_lshlrev_b32_e32 v12, 16, v129
	v_fma_f32 v2, v97, v12, v2
	v_mul_f32_e32 v12, 0x3d372713, v2
	v_mul_f32_e32 v12, v2, v12
	v_fma_f32 v12, v2, v12, v2
	v_mul_f32_e32 v12, 0x3f4c422a, v12
	v_add_f32_e32 v12, v12, v12
	v_mul_f32_e32 v12, 0x3fb8aa3b, v12
	v_exp_f32_e32 v12, v12
	v_add_f32_e32 v19, v19, v19
	v_mul_f32_e32 v19, 0x3fb8aa3b, v19
	v_exp_f32_e32 v19, v19
	v_add_f32_e32 v12, 1.0, v12
	v_rcp_f32_e32 v12, v12
	v_mul_f32_e32 v2, 0.5, v2
	v_add_f32_e32 v19, 1.0, v19
	v_rcp_f32_e32 v19, v19
	v_fma_f32 v12, v12, -2.0, 1.0
	v_add_f32_e32 v12, 1.0, v12
	v_mul_f32_e32 v2, v2, v12
	v_bfe_u32 v12, v2, 16, 1
	v_add3_u32 v2, v2, v12, s45
	s_waitcnt vmcnt(5)
; #define LAS __attribute__((address_space(3)))
; __device__ __forceinline__ unsigned f2bf(float f) { unsigned u = __builtin_bit_cast(unsigned, f); return (u + 0x7fffu + ((u >> 16) & 1u)) >> 16; }
; #define MFMA16(a_, b_, c_) __builtin_amdgcn_mfma_f32_16x16x32_bf16((a_), (b_), (c_), 0, 0, 0)
; #define WAVE_FENCE() asm volatile("s_waitcnt lgkmcnt(0)" ::: "memory")
; template <bool OUT>
; __device__ __forceinline__ void ssm_fast(KArgs ap, int l, LAS unsigned char* lds, const Ctx cx) {
;     ...
;             if (OUT) {
;                 WAVE_FENCE();
;                 const int row = lane & 15, kq = lane >> 4;
; #pragma unroll
;                 for (int tbk = 0; tbk < 2; ++tbk) { f32x4 acc = (f32x4){0.f, 0.f, 0.f, 0.f};
; #pragma unroll
;                     for (int ks = 0; ks < 4; ++ks) { const bf16x8 af = *(const LAS bf16x8*)(BU + (tbk * 16 + row) * 512 + (((ks * 4 + kq) ^ row) << 4)); acc = MFMA16(af, ct[ks], acc); }
; #pragma unroll
;                     for (int j = 0; j < 4; ++j) { const size_t tok = tk + tbk * 16 + 4 * kq + j;
;                         const float uval = bf2f(uv[tbk][j]);
;                         ypre[tok * 512 + g * 16 + row] = (bf16_t)f2bf(gelu_tanh(acc[j] + dsk * uval)); } }
;             }
;         }
;         if (!OUT) { E[(size_t)it * 128 + p] = sr; E[(size_t)it * 128 + 64 + p] = si; }
	v_lshlrev_b32_e32 v12, 16, v127
	v_fmac_f32_e32 v3, v97, v12
	v_mul_f32_e32 v12, 0x3d372713, v3
	v_fma_f32 v0, v19, -2.0, 1.0
	v_mul_f32_e32 v12, v3, v12
	v_mul_f32_e32 v1, 0.5, v1
	v_add_f32_e32 v0, 1.0, v0
	v_fma_f32 v12, v3, v12, v3
	v_mul_f32_e32 v0, v1, v0
	v_mul_f32_e32 v12, 0x3f4c422a, v12
	v_bfe_u32 v1, v0, 16, 1
	v_add_f32_e32 v12, v12, v12
	v_add3_u32 v13, v0, v1, s45
	v_lshlrev_b64 v[0:1], 10, v[26:27]
	v_mul_f32_e32 v12, 0x3fb8aa3b, v12
	v_lshl_add_u64 v[0:1], v[134:135], 0, v[0:1]
	v_exp_f32_e32 v18, v12
	global_store_short_d16_hi v[0:1], v13, off
	v_mov_b32_e32 v1, s9
	v_or_b32_e32 v0, s8, v122
	v_mfma_f32_16x16x32_bf16 v[12:15], v[14:17], v[76:79], 0
	v_lshlrev_b64 v[0:1], 10, v[0:1]
	v_lshl_add_u64 v[0:1], v[134:135], 0, v[0:1]
	global_store_short_d16_hi v[0:1], v2, off
	v_add_f32_e32 v0, 1.0, v18
	v_rcp_f32_e32 v0, v0
	s_waitcnt lgkmcnt(2)
	v_mfma_f32_16x16x32_bf16 v[12:15], v[22:25], v[84:87], v[12:15]
	v_mul_f32_e32 v19, 0.5, v3
	v_mov_b32_e32 v17, s9
	v_fma_f32 v18, v0, -2.0, 1.0
	s_waitcnt lgkmcnt(1)
	v_mfma_f32_16x16x32_bf16 v[0:3], v[8:11], v[88:91], v[12:15]
	v_add_f32_e32 v8, 1.0, v18
	v_or_b32_e32 v16, s8, v124
	v_mul_f32_e32 v8, v19, v8
	s_waitcnt lgkmcnt(0)
	v_mfma_f32_16x16x32_bf16 v[0:3], v[4:7], v[92:95], v[0:3]
	s_waitcnt vmcnt(6)
	v_lshlrev_b32_e32 v4, 16, v125
	v_bfe_u32 v9, v8, 16, 1
	v_add3_u32 v7, v8, v9, s45
	s_nop 3
	v_fma_f32 v0, v97, v4, v0
	v_mul_f32_e32 v4, 0x3d372713, v0
	v_mul_f32_e32 v4, v0, v4
	v_fma_f32 v4, v0, v4, v0
	v_mul_f32_e32 v4, 0x3f4c422a, v4
	v_add_f32_e32 v4, v4, v4
	v_mul_f32_e32 v4, 0x3fb8aa3b, v4
	v_exp_f32_e32 v6, v4
	v_lshlrev_b64 v[4:5], 10, v[16:17]
	v_lshl_add_u64 v[4:5], v[134:135], 0, v[4:5]
	global_store_short_d16_hi v[4:5], v7, off
	v_add_f32_e32 v6, 1.0, v6
	v_rcp_f32_e32 v6, v6
	s_waitcnt vmcnt(6)
	v_lshlrev_b32_e32 v7, 16, v123
	v_fma_f32 v7, v97, v7, v1
	v_mul_f32_e32 v1, 0x3d372713, v7
	v_mul_f32_e32 v1, v7, v1
	v_fma_f32 v6, v6, -2.0, 1.0
	v_fma_f32 v1, v7, v1, v7
	v_mul_f32_e32 v0, 0.5, v0
	v_add_f32_e32 v6, 1.0, v6
	v_mul_f32_e32 v1, 0x3f4c422a, v1
	v_mul_f32_e32 v0, v0, v6
	v_add_f32_e32 v1, v1, v1
	v_mov_b32_e32 v5, s9
	v_or_b32_e32 v4, s8, v104
	v_bfe_u32 v6, v0, 16, 1
	v_mul_f32_e32 v1, 0x3fb8aa3b, v1
	v_exp_f32_e32 v8, v1
	v_add3_u32 v6, v0, v6, s45
	v_lshlrev_b64 v[0:1], 10, v[4:5]
	v_lshl_add_u64 v[0:1], v[134:135], 0, v[0:1]
	global_store_short_d16_hi v[0:1], v6, off
	s_waitcnt vmcnt(6)
	v_lshlrev_b32_e32 v6, 16, v121
	v_fma_f32 v2, v97, v6, v2
	v_mul_f32_e32 v6, 0x3d372713, v2
	v_add_f32_e32 v4, 1.0, v8
	v_mul_f32_e32 v6, v2, v6
	v_rcp_f32_e32 v4, v4
	v_fma_f32 v6, v2, v6, v2
	v_mul_f32_e32 v6, 0x3f4c422a, v6
	v_add_f32_e32 v6, v6, v6
	v_mul_f32_e32 v6, 0x3fb8aa3b, v6
	v_fma_f32 v4, v4, -2.0, 1.0
	v_exp_f32_e32 v6, v6
	v_mul_f32_e32 v5, 0.5, v7
	v_add_f32_e32 v4, 1.0, v4
	v_mul_f32_e32 v4, v5, v4
	v_bfe_u32 v5, v4, 16, 1
	v_add3_u32 v4, v4, v5, s45
	v_add_f32_e32 v5, 1.0, v6
	v_rcp_f32_e32 v5, v5
	v_mov_b32_e32 v1, s9
	v_or_b32_e32 v0, s8, v126
	v_lshlrev_b64 v[0:1], 10, v[0:1]
	v_lshl_add_u64 v[0:1], v[134:135], 0, v[0:1]
	global_store_short_d16_hi v[0:1], v4, off
	v_fma_f32 v4, v5, -2.0, 1.0
	s_waitcnt vmcnt(6)
	v_lshlrev_b32_e32 v5, 16, v119
	v_fmac_f32_e32 v3, v97, v5
	v_mul_f32_e32 v5, 0x3d372713, v3
	v_mul_f32_e32 v5, v3, v5
	v_fma_f32 v5, v3, v5, v3
	v_mul_f32_e32 v5, 0x3f4c422a, v5
	v_add_f32_e32 v5, v5, v5
	v_mul_f32_e32 v5, 0x3fb8aa3b, v5
	v_exp_f32_e32 v5, v5
	v_mul_f32_e32 v2, 0.5, v2
	v_add_f32_e32 v4, 1.0, v4
	v_mul_f32_e32 v2, v2, v4
	v_bfe_u32 v4, v2, 16, 1
	v_add3_u32 v2, v2, v4, s45
	v_add_f32_e32 v4, 1.0, v5
	v_rcp_f32_e32 v4, v4
	v_mov_b32_e32 v1, s9
	v_or_b32_e32 v0, s8, v128
	v_lshlrev_b64 v[0:1], 10, v[0:1]
	v_lshl_add_u64 v[0:1], v[134:135], 0, v[0:1]
	global_store_short_d16_hi v[0:1], v2, off
	v_fma_f32 v2, v4, -2.0, 1.0
	v_mul_f32_e32 v3, 0.5, v3
	v_add_f32_e32 v2, 1.0, v2
	v_mov_b32_e32 v1, s9
	v_or_b32_e32 v0, s8, v130
	v_mul_f32_e32 v2, v3, v2
	v_bfe_u32 v3, v2, 16, 1
	v_lshlrev_b64 v[0:1], 10, v[0:1]
	v_add3_u32 v2, v2, v3, s45
	v_lshl_add_u64 v[0:1], v[134:135], 0, v[0:1]
	global_store_short_d16_hi v[0:1], v2, off
	s_cbranch_scc0 .LBB0_311
	s_add_i32 s0, s0, s7
	s_cmpk_gt_i32 s0, 0x1fff
	s_cbranch_scc0 .LBB0_310

; __device__ __forceinline__ void phase_final(const bf16_t* X, const float* SS, const float* g, float* out, const Ctx cx) {
;     const int wave = cx.wave, lane = cx.lane;
;     const int gw = cx.bid * 8 + wave, NGW = cx.nb * 8;
;     for (int m = gw; m < T; m += NGW) {
;         const float rs = 1.0f / sqrtf(wave_sum(lane < 32 ? SS[(size_t)m * 32 + lane] : 0.f) * (1.0f / DM) + EPS);
; #pragma unroll
;         for (int j = 0; j < 4; ++j) { const u32x4 w = *(const u32x4*)(X + (size_t)m * DM + j * 512 + lane * 8);
;             const f32x4 g0 = *(const f32x4*)(g + j * 512 + lane * 8), g1 = *(const f32x4*)(g + j * 512 + lane * 8 + 4);
.LBB0_844:
	s_mov_b64 s[0:1], s[78:79]
	s_load_dword s0, s[0:1], 0xe0
	s_waitcnt lgkmcnt(0)
	s_cmp_lt_i32 s0, 24
	s_cbranch_scc0 .LBB0_851
	s_mov_b64 s[0:1], s[78:79]
	s_load_dword s0, s[0:1], 0xe4
	s_waitcnt lgkmcnt(0)
	s_cmp_lt_i32 s0, 24
	s_cbranch_scc1 .LBB0_851
	v_readlane_b32 s0, v243, 5
	v_readlane_b32 s8, v243, 0
	v_readlane_b32 s1, v243, 6
	s_load_dword s5, s[0:1], 0x0
	v_readfirstlane_b32 s0, v192
	s_ashr_i32 s4, s0, 6
	s_lshl_b32 s8, s8, 3
	s_add_i32 s4, s4, s8
	s_mov_b64 s[0:1], s[78:79]
	s_mov_b64 s[2:3], s[78:79]
	s_mov_b64 s[6:7], s[78:79]
	s_cmpk_gt_i32 s4, 0x7fff
	s_waitcnt lgkmcnt(0)
	s_cbranch_scc1 .LBB0_851
	v_and_b32_e32 v0, 64, v193
	v_add_u32_e32 v0, 64, v0
	v_xor_b32_e32 v1, 1, v193
	v_cmp_lt_i32_e32 vcc, v1, v0
	s_load_dwordx2 s[10:11], s[0:1], 0xd8
	s_load_dwordx2 s[8:9], s[2:3], 0xd8
	s_load_dwordx2 s[12:13], s[6:7], 0xc8
	v_cndmask_b32_e32 v1, v193, v1, vcc
	v_lshlrev_b32_e32 v12, 2, v1
	v_xor_b32_e32 v1, 2, v193
	v_cmp_lt_i32_e32 vcc, v1, v0
	v_and_b32_e32 v8, 63, v192
	v_lshlrev_b32_e32 v10, 5, v8
	v_cndmask_b32_e32 v1, v193, v1, vcc
	v_lshlrev_b32_e32 v13, 2, v1
	v_xor_b32_e32 v1, 4, v193
	v_cmp_lt_i32_e32 vcc, v1, v0
	v_mov_b32_e32 v11, 0
	s_lshl_b32 s6, s5, 3
	v_cndmask_b32_e32 v1, v193, v1, vcc
	v_lshlrev_b32_e32 v14, 2, v1
	v_xor_b32_e32 v1, 8, v193
	v_cmp_lt_i32_e32 vcc, v1, v0
	s_mov_b64 s[14:15], 0x1800
	s_ashr_i32 s5, s4, 31
	v_cndmask_b32_e32 v1, v193, v1, vcc
	v_lshlrev_b32_e32 v15, 2, v1
	v_xor_b32_e32 v1, 16, v193
	v_cmp_lt_i32_e32 vcc, v1, v0
	v_lshlrev_b32_e32 v6, 2, v8
	v_mov_b32_e32 v7, v11
	v_cndmask_b32_e32 v1, v193, v1, vcc
	v_lshlrev_b32_e32 v16, 2, v1
	v_xor_b32_e32 v1, 32, v193
	v_cmp_lt_i32_e32 vcc, v1, v0
	s_load_dwordx2 s[2:3], s[78:79], 0xd0
	v_cmp_gt_u32_e64 s[0:1], 32, v8
	v_cndmask_b32_e32 v0, v193, v1, vcc
	v_lshlrev_b32_e32 v17, 2, v0
	s_waitcnt lgkmcnt(0)
	v_lshl_add_u64 v[0:1], s[12:13], 0, v[10:11]
	v_lshl_add_u64 v[4:5], v[0:1], 0, s[14:15]
	s_lshl_b64 s[14:15], s[4:5], 7
	s_add_u32 s8, s8, s14
	s_addc_u32 s9, s9, s15
	v_lshl_add_u64 v[6:7], s[8:9], 0, v[6:7]
	s_mov_b64 s[8:9], 0x3f800000
	s_ashr_i32 s7, s6, 31
	v_lshl_add_u64 v[6:7], v[6:7], 0, s[8:9]
	s_lshl_b64 s[8:9], s[6:7], 7
	s_lshl_b64 s[14:15], s[4:5], 12
	s_add_u32 s10, s10, s14
	v_lshlrev_b32_e32 v8, 4, v8
	v_mov_b32_e32 v9, v11
	s_addc_u32 s11, s11, s15
	v_lshl_add_u64 v[8:9], s[10:11], 0, v[8:9]
	s_mov_b64 s[10:11], 0xb000000
	v_lshl_add_u64 v[8:9], v[8:9], 0, s[10:11]
	s_lshl_b64 s[10:11], s[6:7], 12
	s_lshl_b64 s[14:15], s[4:5], 13
	s_add_u32 s2, s2, s14
	s_addc_u32 s3, s3, s15
	s_mov_b64 s[12:13], 0x1000
	v_lshl_add_u64 v[10:11], s[2:3], 0, v[10:11]
	v_lshl_add_u64 v[2:3], v[0:1], 0, s[12:13]
	v_lshl_add_u64 v[10:11], v[10:11], 0, s[12:13]
	s_lshl_b64 s[12:13], s[6:7], 13
	v_mov_b32_e32 v18, 0x3727c5ac
	s_mov_b32 s5, 0xf800000
	v_mov_b32_e32 v19, 0x260
	global_load_dwordx4 v[50:53], v[0:1], off
	global_load_dwordx4 v[54:57], v[0:1], off offset:16
	global_load_dwordx4 v[58:61], v[0:1], off offset:2048
	global_load_dwordx4 v[62:65], v[0:1], off offset:2064
	global_load_dwordx4 v[66:69], v[2:3], off
	global_load_dwordx4 v[70:73], v[2:3], off offset:16
	global_load_dwordx4 v[74:77], v[4:5], off
	global_load_dwordx4 v[78:81], v[4:5], off offset:16
	s_branch .LBB0_849
; __device__ __forceinline__ void phase_final(const bf16_t* X, const float* SS, const float* g, float* out, const Ctx cx) {
;     ...
;     for (int m = gw; m < T; m += NGW) {
;         const float rs = 1.0f / sqrtf(wave_sum(lane < 32 ? SS[(size_t)m * 32 + lane] : 0.f) * (1.0f / DM) + EPS);
; #pragma unroll
;         for (int j = 0; j < 4; ++j) { const u32x4 w = *(const u32x4*)(X + (size_t)m * DM + j * 512 + lane * 8);
;             const f32x4 g0 = *(const f32x4*)(g + j * 512 + lane * 8), g1 = *(const f32x4*)(g + j * 512 + lane * 8 + 4);
;             f32x4 o0, o1; o0.x = bflo(w.x) * rs * g0.x; o0.y = bfhi(w.x) * rs * g0.y; o0.z = bflo(w.y) * rs * g0.z; o0.w = bfhi(w.y) * rs * g0.w;
;             o1.x = bflo(w.z) * rs * g1.x; o1.y = bfhi(w.z) * rs * g1.y; o1.z = bflo(w.w) * rs * g1.z; o1.w = bfhi(w.w) * rs * g1.w;
;             float* op = out + (size_t)m * DM + j * 512 + lane * 8; *(f32x4*)op = o0; *(f32x4*)(op + 4) = o1; }
;     }
.LBB0_848:
	s_or_b64 exec, exec, s[2:3]
	global_load_dwordx4 v[90:93], v[8:9], off
	global_load_dwordx4 v[94:97], v[8:9], off offset:1024
	global_load_dwordx4 v[98:101], v[8:9], off offset:2048
	global_load_dwordx4 v[102:105], v[8:9], off offset:3072
	s_waitcnt vmcnt(3)
	v_mov_b32_e32 v22, v90
	v_mov_b32_e32 v23, v91
	v_mov_b32_e32 v24, v92
	v_mov_b32_e32 v25, v93
	v_mov_b32_e32 v26, v50
	v_mov_b32_e32 v27, v51
	v_mov_b32_e32 v28, v52
	v_mov_b32_e32 v29, v53
	v_mov_b32_e32 v30, v54
	v_mov_b32_e32 v31, v55
	v_mov_b32_e32 v32, v56
	v_mov_b32_e32 v33, v57
	ds_bpermute_b32 v21, v12, v20
	s_add_i32 s4, s4, s6
	v_lshl_add_u64 v[6:7], v[6:7], 0, s[8:9]
	s_cmp_lt_i32 s4, 0x8000
	s_waitcnt lgkmcnt(0)
	v_add_f32_e32 v20, v20, v21
	ds_bpermute_b32 v21, v13, v20
	s_waitcnt lgkmcnt(0)
	v_add_f32_e32 v20, v20, v21
	ds_bpermute_b32 v21, v14, v20
	s_waitcnt lgkmcnt(0)
	v_add_f32_e32 v20, v20, v21
	ds_bpermute_b32 v21, v15, v20
	s_waitcnt lgkmcnt(0)
	v_add_f32_e32 v20, v20, v21
	ds_bpermute_b32 v21, v16, v20
	s_waitcnt lgkmcnt(0)
	v_add_f32_e32 v20, v20, v21
	ds_bpermute_b32 v21, v17, v20
	s_waitcnt lgkmcnt(0)
	v_add_f32_e32 v20, v20, v21
	v_fmamk_f32 v20, v20, 0x3a000000, v18
	v_mul_f32_e32 v21, 0x4f800000, v20
	v_cmp_gt_f32_e32 vcc, s5, v20
	s_nop 1
	v_cndmask_b32_e32 v20, v20, v21, vcc
	v_sqrt_f32_e32 v21, v20
	s_nop 0
	v_add_u32_e32 v34, -1, v21
	v_add_u32_e32 v35, 1, v21
	v_fma_f32 v36, -v34, v21, v20
	v_fma_f32 v37, -v35, v21, v20
	v_cmp_ge_f32_e64 s[2:3], 0, v36
	s_nop 1
	v_cndmask_b32_e64 v21, v21, v34, s[2:3]
	v_cmp_lt_f32_e64 s[2:3], 0, v37
	s_nop 1
	v_cndmask_b32_e64 v21, v21, v35, s[2:3]
	v_mul_f32_e32 v34, 0x37800000, v21
	v_cndmask_b32_e32 v21, v21, v34, vcc
	v_cmp_class_f32_e32 vcc, v20, v19
	s_nop 1
	v_cndmask_b32_e32 v20, v21, v20, vcc
	v_div_scale_f32 v21, s[2:3], v20, v20, 1.0
	v_rcp_f32_e32 v34, v21
	v_div_scale_f32 v35, vcc, 1.0, v20, 1.0
	v_fma_f32 v36, -v21, v34, 1.0
	v_fmac_f32_e32 v34, v36, v34
	v_mul_f32_e32 v36, v35, v34
	v_fma_f32 v37, -v21, v36, v35
	v_fmac_f32_e32 v36, v37, v34
	v_fma_f32 v21, -v21, v36, v35
	v_div_fmas_f32 v21, v21, v34, v36
	v_div_fixup_f32 v34, v21, v20, 1.0
	v_lshlrev_b32_e32 v20, 16, v22
	v_and_b32_e32 v21, 0xffff0000, v22
	v_lshlrev_b32_e32 v22, 16, v23
	v_and_b32_e32 v23, 0xffff0000, v23
	v_lshlrev_b32_e32 v36, 16, v24
	v_and_b32_e32 v37, 0xffff0000, v24
	v_lshlrev_b32_e32 v24, 16, v25
	v_and_b32_e32 v25, 0xffff0000, v25
	v_pk_mul_f32 v[20:21], v[34:35], v[20:21] op_sel_hi:[0,1]
	v_pk_mul_f32 v[22:23], v[34:35], v[22:23] op_sel_hi:[0,1]
	v_pk_mul_f32 v[36:37], v[34:35], v[36:37] op_sel_hi:[0,1]
	v_pk_mul_f32 v[38:39], v[34:35], v[24:25] op_sel_hi:[0,1]
	v_pk_mul_f32 v[20:21], v[26:27], v[20:21]
	v_pk_mul_f32 v[22:23], v[28:29], v[22:23]
	v_pk_mul_f32 v[24:25], v[30:31], v[36:37]
	v_pk_mul_f32 v[26:27], v[32:33], v[38:39]
	global_store_dwordx4 v[10:11], v[20:23], off offset:-4096
	global_store_dwordx4 v[10:11], v[24:27], off offset:-4080
	s_nop 0
	s_waitcnt vmcnt(4)
	v_mov_b32_e32 v20, v94
	v_mov_b32_e32 v21, v95
	v_mov_b32_e32 v22, v96
	v_mov_b32_e32 v23, v97
	v_lshlrev_b32_e32 v32, 16, v20
	v_and_b32_e32 v33, 0xffff0000, v20
	v_lshlrev_b32_e32 v20, 16, v21
	v_and_b32_e32 v21, 0xffff0000, v21
	v_lshlrev_b32_e32 v36, 16, v22
	v_and_b32_e32 v37, 0xffff0000, v22
	v_lshlrev_b32_e32 v22, 16, v23
	v_and_b32_e32 v23, 0xffff0000, v23
	v_pk_mul_f32 v[32:33], v[34:35], v[32:33] op_sel_hi:[0,1]
	v_pk_mul_f32 v[38:39], v[34:35], v[20:21] op_sel_hi:[0,1]
	v_pk_mul_f32 v[36:37], v[34:35], v[36:37] op_sel_hi:[0,1]
	v_pk_mul_f32 v[40:41], v[34:35], v[22:23] op_sel_hi:[0,1]
	v_mov_b32_e32 v24, v58
	v_mov_b32_e32 v25, v59
	v_mov_b32_e32 v26, v60
	v_mov_b32_e32 v27, v61
	v_pk_mul_f32 v[20:21], v[24:25], v[32:33]
	v_pk_mul_f32 v[22:23], v[26:27], v[38:39]
	v_mov_b32_e32 v28, v62
	v_mov_b32_e32 v29, v63
	v_mov_b32_e32 v30, v64
	v_mov_b32_e32 v31, v65
	v_pk_mul_f32 v[24:25], v[28:29], v[36:37]
	v_pk_mul_f32 v[26:27], v[30:31], v[40:41]
	global_store_dwordx4 v[10:11], v[20:23], off offset:-2048
	global_store_dwordx4 v[10:11], v[24:27], off offset:-2032
	s_nop 0
	s_waitcnt vmcnt(5)
	v_mov_b32_e32 v20, v98
	v_mov_b32_e32 v21, v99
	v_mov_b32_e32 v22, v100
	v_mov_b32_e32 v23, v101
	v_lshlrev_b32_e32 v32, 16, v20
	v_and_b32_e32 v33, 0xffff0000, v20
	v_lshlrev_b32_e32 v20, 16, v21
	v_and_b32_e32 v21, 0xffff0000, v21
	v_lshlrev_b32_e32 v36, 16, v22
	v_and_b32_e32 v37, 0xffff0000, v22
	v_lshlrev_b32_e32 v22, 16, v23
	v_and_b32_e32 v23, 0xffff0000, v23
	v_pk_mul_f32 v[32:33], v[34:35], v[32:33] op_sel_hi:[0,1]
	v_pk_mul_f32 v[38:39], v[34:35], v[20:21] op_sel_hi:[0,1]
	v_pk_mul_f32 v[36:37], v[34:35], v[36:37] op_sel_hi:[0,1]
	v_pk_mul_f32 v[40:41], v[34:35], v[22:23] op_sel_hi:[0,1]
	v_mov_b32_e32 v24, v66
	v_mov_b32_e32 v25, v67
	v_mov_b32_e32 v26, v68
	v_mov_b32_e32 v27, v69
	v_pk_mul_f32 v[20:21], v[24:25], v[32:33]
	v_pk_mul_f32 v[22:23], v[26:27], v[38:39]
	v_mov_b32_e32 v28, v70
	v_mov_b32_e32 v29, v71
	v_mov_b32_e32 v30, v72
	v_mov_b32_e32 v31, v73
	v_pk_mul_f32 v[24:25], v[28:29], v[36:37]
	v_pk_mul_f32 v[26:27], v[30:31], v[40:41]
	global_store_dwordx4 v[10:11], v[20:23], off
	global_store_dwordx4 v[10:11], v[24:27], off offset:16
	s_nop 0
	v_lshl_add_u64 v[8:9], v[8:9], 0, s[10:11]
	s_waitcnt vmcnt(6)
	v_mov_b32_e32 v20, v102
	v_mov_b32_e32 v21, v103
	v_mov_b32_e32 v22, v104
	v_mov_b32_e32 v23, v105
	v_lshlrev_b32_e32 v32, 16, v20
	v_and_b32_e32 v33, 0xffff0000, v20
	v_lshlrev_b32_e32 v20, 16, v21
	v_and_b32_e32 v21, 0xffff0000, v21
	v_lshlrev_b32_e32 v36, 16, v22
	v_and_b32_e32 v37, 0xffff0000, v22
	v_lshlrev_b32_e32 v22, 16, v23
	v_and_b32_e32 v23, 0xffff0000, v23
	v_pk_mul_f32 v[32:33], v[34:35], v[32:33] op_sel_hi:[0,1]
	v_pk_mul_f32 v[38:39], v[34:35], v[20:21] op_sel_hi:[0,1]
	v_pk_mul_f32 v[36:37], v[34:35], v[36:37] op_sel_hi:[0,1]
	v_pk_mul_f32 v[34:35], v[34:35], v[22:23] op_sel_hi:[0,1]
	v_mov_b32_e32 v24, v74
	v_mov_b32_e32 v25, v75
	v_mov_b32_e32 v26, v76
	v_mov_b32_e32 v27, v77
	v_pk_mul_f32 v[20:21], v[24:25], v[32:33]
	v_pk_mul_f32 v[22:23], v[26:27], v[38:39]
	v_mov_b32_e32 v28, v78
	v_mov_b32_e32 v29, v79
	v_mov_b32_e32 v30, v80
	v_mov_b32_e32 v31, v81
	v_pk_mul_f32 v[24:25], v[28:29], v[36:37]
	v_pk_mul_f32 v[26:27], v[30:31], v[34:35]
	global_store_dwordx4 v[10:11], v[20:23], off offset:2048
	global_store_dwordx4 v[10:11], v[24:27], off offset:2064
	v_lshl_add_u64 v[10:11], v[10:11], 0, s[12:13]
	s_cbranch_scc0 .LBB0_851
